# attention: K/V tile prefetched two iterations ahead (second register set), QK/PV LDS reads hoisted; scan pipelined; rstd batched
# speedup vs baseline: 1.0005x; 1.0005x over previous
.LBB0_177:
	s_waitcnt vmcnt(8)
	v_lshlrev_b32_e32 v1, 16, v86
	v_mul_f32_e32 v38, 0xbfb8aa3b, v1
	v_exp_f32_e32 v38, v38
	v_lshlrev_b64 v[2:3], 13, v[88:89]
	v_lshl_add_u64 v[2:3], s[76:77], 0, v[2:3]
	v_lshl_add_u64 v[2:3], v[2:3], 0, s[52:53]
	v_add_f32_e32 v38, 1.0, v38
	v_rcp_f32_e32 v38, v38
	v_lshlrev_b32_e32 v36, 1, v92
	v_mov_b32_e32 v37, v0
	v_lshl_add_u64 v[36:37], v[2:3], 0, v[36:37]
	v_mul_f32_e32 v1, v38, v1
	v_mul_f32_e32 v1, v1, v32
	v_and_b32_e32 v32, 0xffff0000, v86
	v_mul_f32_e32 v38, 0xbfb8aa3b, v32
	v_exp_f32_e32 v38, v38
	s_mov_b64 s[12:13], 0x24181000
	v_lshl_add_u64 v[2:3], v[36:37], 0, s[12:13]
	s_mov_b32 s12, 0x24181000
	v_add_f32_e32 v38, 1.0, v38
	v_rcp_f32_e32 v38, v38
	s_add_i32 s24, s24, s3
	s_mov_b32 s25, 0x10000
	s_cmpk_gt_i32 s24, 0x3ff
	v_mul_f32_e32 v32, v38, v32
	v_mul_f32_e32 v32, v32, v33
	v_cvt_pk_bf16_f32 v32, v1, v32
	v_lshlrev_b32_e32 v1, 16, v87
	v_mul_f32_e32 v33, 0xbfb8aa3b, v1
	v_exp_f32_e32 v33, v33
	s_nop 0
	v_add_f32_e32 v33, 1.0, v33
	v_rcp_f32_e32 v33, v33
	s_nop 0
	v_mul_f32_e32 v1, v33, v1
	v_and_b32_e32 v33, 0xffff0000, v87
	v_mul_f32_e32 v1, v1, v34
	v_mul_f32_e32 v34, 0xbfb8aa3b, v33
	v_exp_f32_e32 v34, v34
	s_nop 0
	v_add_f32_e32 v34, 1.0, v34
	v_rcp_f32_e32 v34, v34
	s_nop 0
	v_mul_f32_e32 v33, v34, v33
	v_mul_f32_e32 v33, v33, v35
	v_add_co_u32_e32 v34, vcc, s12, v36
	v_cvt_pk_bf16_f32 v33, v1, v33
	s_waitcnt vmcnt(6)
	v_lshlrev_b32_e32 v1, 16, v84
	v_addc_co_u32_e32 v35, vcc, 0, v37, vcc
	global_store_dwordx2 v[34:35], v[32:33], off
	v_mul_f32_e32 v32, 0xbfb8aa3b, v1
	v_exp_f32_e32 v32, v32
	s_nop 0
	v_add_f32_e32 v32, 1.0, v32
	v_rcp_f32_e32 v32, v32
	s_nop 0
	v_mul_f32_e32 v1, v32, v1
	v_mul_f32_e32 v1, v1, v28
	v_and_b32_e32 v28, 0xffff0000, v84
	v_mul_f32_e32 v32, 0xbfb8aa3b, v28
	v_exp_f32_e32 v32, v32
	s_nop 0
	v_add_f32_e32 v32, 1.0, v32
	v_rcp_f32_e32 v32, v32
	s_nop 0
	v_mul_f32_e32 v28, v32, v28
	v_mul_f32_e32 v28, v28, v29
	v_cvt_pk_bf16_f32 v28, v1, v28
	v_lshlrev_b32_e32 v1, 16, v85
	v_mul_f32_e32 v29, 0xbfb8aa3b, v1
	v_exp_f32_e32 v29, v29
	s_nop 0
	v_add_f32_e32 v29, 1.0, v29
	v_rcp_f32_e32 v29, v29
	s_nop 0
	v_mul_f32_e32 v1, v29, v1
	v_and_b32_e32 v29, 0xffff0000, v85
	v_mul_f32_e32 v1, v1, v30
	v_mul_f32_e32 v30, 0xbfb8aa3b, v29
	v_exp_f32_e32 v30, v30
	s_nop 0
	v_add_f32_e32 v30, 1.0, v30
	v_rcp_f32_e32 v30, v30
	s_nop 0
	v_mul_f32_e32 v29, v30, v29
	v_mul_f32_e32 v29, v29, v31
	v_cvt_pk_bf16_f32 v29, v1, v29
	s_waitcnt vmcnt(6)
	v_lshlrev_b32_e32 v1, 16, v82
	global_store_dwordx2 v[2:3], v[28:29], off offset:32
	v_mul_f32_e32 v28, 0xbfb8aa3b, v1
	v_exp_f32_e32 v28, v28
	s_nop 0
	v_add_f32_e32 v28, 1.0, v28
	v_rcp_f32_e32 v28, v28
	s_nop 0
	v_mul_f32_e32 v1, v28, v1
	v_mul_f32_e32 v1, v1, v24
	v_and_b32_e32 v24, 0xffff0000, v82
	v_mul_f32_e32 v28, 0xbfb8aa3b, v24
	v_exp_f32_e32 v28, v28
	s_nop 0
	v_add_f32_e32 v28, 1.0, v28
	v_rcp_f32_e32 v28, v28
	s_nop 0
	v_mul_f32_e32 v24, v28, v24
	v_mul_f32_e32 v24, v24, v25
	v_cvt_pk_bf16_f32 v24, v1, v24
	v_lshlrev_b32_e32 v1, 16, v83
	v_mul_f32_e32 v25, 0xbfb8aa3b, v1
	v_exp_f32_e32 v25, v25
	s_nop 0
	v_add_f32_e32 v25, 1.0, v25
	v_rcp_f32_e32 v25, v25
	s_nop 0
	v_mul_f32_e32 v1, v25, v1
	v_and_b32_e32 v25, 0xffff0000, v83
	v_mul_f32_e32 v1, v1, v26
	v_mul_f32_e32 v26, 0xbfb8aa3b, v25
	v_exp_f32_e32 v26, v26
	s_nop 0
	v_add_f32_e32 v26, 1.0, v26
	v_rcp_f32_e32 v26, v26
	s_nop 0
	v_mul_f32_e32 v25, v26, v25
	v_mul_f32_e32 v25, v25, v27
	v_cvt_pk_bf16_f32 v25, v1, v25
	s_waitcnt vmcnt(6)
	v_lshlrev_b32_e32 v1, 16, v80
	global_store_dwordx2 v[2:3], v[24:25], off offset:64
	v_mul_f32_e32 v24, 0xbfb8aa3b, v1
	v_exp_f32_e32 v24, v24
	s_nop 0
	v_add_f32_e32 v24, 1.0, v24
	v_rcp_f32_e32 v24, v24
	s_nop 0
	v_mul_f32_e32 v1, v24, v1
	v_mul_f32_e32 v1, v1, v20
	v_and_b32_e32 v20, 0xffff0000, v80
	v_mul_f32_e32 v24, 0xbfb8aa3b, v20
	v_exp_f32_e32 v24, v24
	s_nop 0
	v_add_f32_e32 v24, 1.0, v24
	v_rcp_f32_e32 v24, v24
	s_nop 0
	v_mul_f32_e32 v20, v24, v20
	v_mul_f32_e32 v20, v20, v21
	v_cvt_pk_bf16_f32 v20, v1, v20
	v_lshlrev_b32_e32 v1, 16, v81
	v_mul_f32_e32 v21, 0xbfb8aa3b, v1
	v_exp_f32_e32 v21, v21
	s_nop 0
	v_add_f32_e32 v21, 1.0, v21
	v_rcp_f32_e32 v21, v21
	s_nop 0
	v_mul_f32_e32 v1, v21, v1
	v_and_b32_e32 v21, 0xffff0000, v81
	v_mul_f32_e32 v1, v1, v22
	v_mul_f32_e32 v22, 0xbfb8aa3b, v21
	v_exp_f32_e32 v22, v22
	s_nop 0
	v_add_f32_e32 v22, 1.0, v22
	v_rcp_f32_e32 v22, v22
	s_nop 0
	v_mul_f32_e32 v21, v22, v21
	v_mul_f32_e32 v21, v21, v23
	v_cvt_pk_bf16_f32 v21, v1, v21
	s_waitcnt vmcnt(6)
	v_lshlrev_b32_e32 v1, 16, v78
	global_store_dwordx2 v[2:3], v[20:21], off offset:96
	v_mul_f32_e32 v20, 0xbfb8aa3b, v1
	v_exp_f32_e32 v20, v20
	s_nop 0
	v_add_f32_e32 v20, 1.0, v20
	v_rcp_f32_e32 v20, v20
	s_nop 0
	v_mul_f32_e32 v1, v20, v1
	v_mul_f32_e32 v1, v1, v16
	v_and_b32_e32 v16, 0xffff0000, v78
	v_mul_f32_e32 v20, 0xbfb8aa3b, v16
	v_exp_f32_e32 v20, v20
	s_nop 0
	v_add_f32_e32 v20, 1.0, v20
	v_rcp_f32_e32 v20, v20
	s_nop 0
	v_mul_f32_e32 v16, v20, v16
	v_mul_f32_e32 v16, v16, v17
	v_cvt_pk_bf16_f32 v16, v1, v16
	v_lshlrev_b32_e32 v1, 16, v79
	v_mul_f32_e32 v17, 0xbfb8aa3b, v1
	v_exp_f32_e32 v17, v17
	s_nop 0
	v_add_f32_e32 v17, 1.0, v17
	v_rcp_f32_e32 v17, v17
	s_nop 0
	v_mul_f32_e32 v1, v17, v1
	v_and_b32_e32 v17, 0xffff0000, v79
	v_mul_f32_e32 v1, v1, v18
	v_mul_f32_e32 v18, 0xbfb8aa3b, v17
	v_exp_f32_e32 v18, v18
	s_nop 0
	v_add_f32_e32 v18, 1.0, v18
	v_rcp_f32_e32 v18, v18
	s_nop 0
	v_mul_f32_e32 v17, v18, v17
	v_mul_f32_e32 v17, v17, v19
	v_cvt_pk_bf16_f32 v17, v1, v17
	s_waitcnt vmcnt(6)
	v_lshlrev_b32_e32 v1, 16, v76
	global_store_dwordx2 v[2:3], v[16:17], off offset:128
	v_mul_f32_e32 v16, 0xbfb8aa3b, v1
	v_exp_f32_e32 v16, v16
	s_nop 0
	v_add_f32_e32 v16, 1.0, v16
	v_rcp_f32_e32 v16, v16
	s_nop 0
	v_mul_f32_e32 v1, v16, v1
	v_mul_f32_e32 v1, v1, v12
	v_and_b32_e32 v12, 0xffff0000, v76
	v_mul_f32_e32 v16, 0xbfb8aa3b, v12
	v_exp_f32_e32 v16, v16
	s_nop 0
	v_add_f32_e32 v16, 1.0, v16
	v_rcp_f32_e32 v16, v16
	s_nop 0
	v_mul_f32_e32 v12, v16, v12
	v_mul_f32_e32 v12, v12, v13
	v_cvt_pk_bf16_f32 v12, v1, v12
	v_lshlrev_b32_e32 v1, 16, v77
	v_mul_f32_e32 v13, 0xbfb8aa3b, v1
	v_exp_f32_e32 v13, v13
	s_nop 0
	v_add_f32_e32 v13, 1.0, v13
	v_rcp_f32_e32 v13, v13
	s_nop 0
	v_mul_f32_e32 v1, v13, v1
	v_and_b32_e32 v13, 0xffff0000, v77
	v_mul_f32_e32 v1, v1, v14
	v_mul_f32_e32 v14, 0xbfb8aa3b, v13
	v_exp_f32_e32 v14, v14
	s_nop 0
	v_add_f32_e32 v14, 1.0, v14
	v_rcp_f32_e32 v14, v14
	s_nop 0
	v_mul_f32_e32 v13, v14, v13
	v_mul_f32_e32 v13, v13, v15
	v_cvt_pk_bf16_f32 v13, v1, v13
	s_waitcnt vmcnt(6)
	v_lshlrev_b32_e32 v1, 16, v74
	global_store_dwordx2 v[2:3], v[12:13], off offset:160
	v_mul_f32_e32 v12, 0xbfb8aa3b, v1
	v_exp_f32_e32 v12, v12
	s_nop 0
	v_add_f32_e32 v12, 1.0, v12
	v_rcp_f32_e32 v12, v12
	s_nop 0
	v_mul_f32_e32 v1, v12, v1
	v_mul_f32_e32 v1, v1, v8
	v_and_b32_e32 v8, 0xffff0000, v74
	v_mul_f32_e32 v12, 0xbfb8aa3b, v8
	v_exp_f32_e32 v12, v12
	s_nop 0
	v_add_f32_e32 v12, 1.0, v12
	v_rcp_f32_e32 v12, v12
	s_nop 0
	v_mul_f32_e32 v8, v12, v8
	v_mul_f32_e32 v8, v8, v9
	v_cvt_pk_bf16_f32 v8, v1, v8
	v_lshlrev_b32_e32 v1, 16, v75
	v_mul_f32_e32 v9, 0xbfb8aa3b, v1
	v_exp_f32_e32 v9, v9
	s_nop 0
	v_add_f32_e32 v9, 1.0, v9
	v_rcp_f32_e32 v9, v9
	s_nop 0
	v_mul_f32_e32 v1, v9, v1
	v_and_b32_e32 v9, 0xffff0000, v75
	v_mul_f32_e32 v1, v1, v10
	v_mul_f32_e32 v10, 0xbfb8aa3b, v9
	v_exp_f32_e32 v10, v10
	s_nop 0
	v_add_f32_e32 v10, 1.0, v10
	v_rcp_f32_e32 v10, v10
	s_nop 0
	v_mul_f32_e32 v9, v10, v9
	v_mul_f32_e32 v9, v9, v11
	v_cvt_pk_bf16_f32 v9, v1, v9
	s_waitcnt vmcnt(6)
	v_lshlrev_b32_e32 v1, 16, v72
	global_store_dwordx2 v[2:3], v[8:9], off offset:192
	v_mul_f32_e32 v8, 0xbfb8aa3b, v1
	v_exp_f32_e32 v8, v8
	s_nop 0
	v_add_f32_e32 v8, 1.0, v8
	v_rcp_f32_e32 v8, v8
	s_nop 0
	v_mul_f32_e32 v1, v8, v1
	v_mul_f32_e32 v1, v1, v4
	v_and_b32_e32 v4, 0xffff0000, v72
	v_mul_f32_e32 v8, 0xbfb8aa3b, v4
	v_exp_f32_e32 v8, v8
	s_nop 0
	v_add_f32_e32 v8, 1.0, v8
	v_rcp_f32_e32 v8, v8
	s_nop 0
	v_mul_f32_e32 v4, v8, v4
	v_mul_f32_e32 v4, v4, v5
	v_cvt_pk_bf16_f32 v4, v1, v4
	v_lshlrev_b32_e32 v1, 16, v73
	v_mul_f32_e32 v5, 0xbfb8aa3b, v1
	v_exp_f32_e32 v5, v5
	s_nop 0
	v_add_f32_e32 v5, 1.0, v5
	v_rcp_f32_e32 v5, v5
	s_nop 0
	v_mul_f32_e32 v1, v5, v1
	v_and_b32_e32 v5, 0xffff0000, v73
	v_mul_f32_e32 v1, v1, v6
	v_mul_f32_e32 v6, 0xbfb8aa3b, v5
	v_exp_f32_e32 v6, v6
	s_nop 0
	v_add_f32_e32 v6, 1.0, v6
	v_rcp_f32_e32 v6, v6
	s_nop 0
	v_mul_f32_e32 v5, v6, v5
	v_mul_f32_e32 v5, v5, v7
	v_cvt_pk_bf16_f32 v5, v1, v5
	global_store_dwordx2 v[2:3], v[4:5], off offset:224
	s_barrier
	s_cbranch_scc1 .LBB0_37
.LBB0_178:
	s_ashr_i32 s12, s24, 4
	v_mov_b32_e32 v1, v220
	s_lshl_b32 s25, s12, 7
	v_ashrrev_i32_e32 v6, 6, v1
	v_and_b32_e32 v4, 15, v1
	s_waitcnt lgkmcnt(0)
	v_lshl_add_u32 v7, v6, 4, s25
	s_lshl_b32 s13, s24, 7
	v_or_b32_e32 v88, v7, v4
	v_mov_b64_e32 v[2:3], s[84:85]
	s_and_b32 s13, s13, 0x780
	v_bfe_u32 v5, v1, 4, 2
	v_mad_i64_i32 v[2:3], s[16:17], v88, s11, v[2:3]
	s_lshl_b32 s52, s13, 1
	v_lshl_add_u64 v[2:3], v[2:3], 0, s[52:53]
	v_lshlrev_b32_e32 v8, 3, v5
	v_mov_b32_e32 v9, v0
	v_lshl_add_u64 v[8:9], v[2:3], 0, v[8:9]
	s_mov_b64 s[16:17], 0x5800
	v_lshl_add_u64 v[10:11], v[8:9], 0, s[16:17]
	v_add_co_u32_e32 v8, vcc, 0x5000, v8
	v_ashrrev_i32_e32 v89, 31, v88
	s_nop 0
	v_addc_co_u32_e32 v9, vcc, 0, v9, vcc
	global_load_dwordx2 v[86:87], v[8:9], off offset:2048
	global_load_dwordx2 v[84:85], v[10:11], off offset:32
	global_load_dwordx2 v[82:83], v[10:11], off offset:64
	global_load_dwordx2 v[80:81], v[10:11], off offset:96
	global_load_dwordx2 v[78:79], v[10:11], off offset:128
	global_load_dwordx2 v[76:77], v[10:11], off offset:160
	global_load_dwordx2 v[74:75], v[10:11], off offset:192
	global_load_dwordx2 v[72:73], v[10:11], off offset:224
	v_lshlrev_b32_e32 v92, 2, v5
	s_cmp_lt_i32 s12, 0
	s_cbranch_scc1 .LBB0_176
	v_or_b32_e32 v93, 14, v7
	v_and_b32_e32 v7, 16, v1
	v_cmp_eq_u32_e32 vcc, 0, v7
	v_lshlrev_b32_e32 v7, 3, v1
	v_and_b32_e32 v11, 0x78, v7
	v_readlane_b32 s13, v244, 26
	s_add_u32 s16, s84, s52
	v_and_b32_e32 v10, 63, v1
	v_lshl_add_u32 v96, v6, 2, s13
	s_addc_u32 s17, s85, 0
	v_lshlrev_b32_e32 v6, 1, v11
	v_mov_b32_e32 v7, v0
	v_lshlrev_b32_e32 v8, 4, v5
	v_mov_b32_e32 v9, v0
	v_cndmask_b32_e64 v94, 0, 1.0, vcc
	v_cmp_gt_u32_e32 vcc, 32, v10
	v_lshl_add_u64 v[90:91], s[16:17], 0, v[6:7]
	v_lshl_add_u64 v[2:3], v[2:3], 0, v[8:9]
	s_mov_b64 s[16:17], 0x2800
	s_movk_i32 s13, 0x2000
	v_cndmask_b32_e64 v95, 0, 1.0, vcc
	v_lshl_add_u64 v[8:9], v[2:3], 0, s[16:17]
	v_add_co_u32_e32 v2, vcc, s13, v2
	s_lshl_b32 s16, s12, 1
	s_nop 0
	v_addc_co_u32_e32 v3, vcc, 0, v3, vcc
	s_lshl_b32 s12, s12, 7
	v_ashrrev_i32_e32 v97, 4, v1
	global_load_dwordx4 v[36:39], v[8:9], off offset:192
	global_load_dwordx4 v[40:43], v[8:9], off offset:128
	global_load_dwordx4 v[44:47], v[8:9], off offset:64
	global_load_dwordx4 v[48:51], v[2:3], off offset:2048
	v_add3_u32 v5, v97, s12, 64
	v_mov_b64_e32 v[2:3], s[84:85]
	v_mad_i64_i32 v[2:3], s[12:13], v5, s11, v[2:3]
	v_lshl_add_u64 v[2:3], v[2:3], 0, s[52:53]
	v_lshl_add_u64 v[2:3], v[2:3], 0, v[6:7]
	s_mov_b32 s12, 0xd4000
	v_add_co_u32_e32 v6, vcc, s12, v2
	s_mov_b32 s12, 0xd3000
	s_nop 0
	v_addc_co_u32_e32 v7, vcc, 0, v3, vcc
	global_load_dwordx4 v[52:55], v[6:7], off offset:2048
	v_add_co_u32_e32 v6, vcc, s12, v2
	s_movk_i32 s12, 0x4000
	s_nop 0
	v_addc_co_u32_e32 v7, vcc, 0, v3, vcc
	global_load_dwordx4 v[60:63], v[6:7], off offset:2048
	v_add_co_u32_e32 v6, vcc, s12, v2
	s_movk_i32 s12, 0x3000
	s_nop 0
	v_addc_co_u32_e32 v7, vcc, 0, v3, vcc
	v_add_co_u32_e32 v2, vcc, s12, v2
	global_load_dwordx4 v[56:59], v[6:7], off offset:2048
	s_nop 0
	v_addc_co_u32_e32 v3, vcc, 0, v3, vcc
	global_load_dwordx4 v[64:67], v[2:3], off offset:2048
	v_add_co_u32_e32 v200, vcc, 0xffe60000, v2
	s_nop 1
	v_addc_co_u32_e32 v201, vcc, -1, v3, vcc
	v_add_co_u32_e32 v202, vcc, 0x1000, v200
	s_nop 1
	v_addc_co_u32_e32 v203, vcc, 0, v201, vcc
	v_add_co_u32_e32 v204, vcc, 0xd0000, v200
	s_nop 1
	v_addc_co_u32_e32 v205, vcc, 0, v201, vcc
	global_load_dwordx4 v[216:219], v[200:201], off offset:2048
	global_load_dwordx4 v[232:235], v[202:203], off offset:2048
	global_load_dwordx4 v[236:239], v[204:205], off offset:2048
	v_add_co_u32_e32 v204, vcc, 0x1000, v204
	s_nop 1
	v_addc_co_u32_e32 v205, vcc, 0, v205, vcc
	global_load_dwordx4 v[240:243], v[204:205], off offset:2048
	v_mul_lo_u32 v2, v97, s82
	v_add_lshl_u32 v98, v2, v11, 1
	v_lshrrev_b32_e32 v2, 2, v4
	v_and_b32_e32 v100, 48, v1
	v_or_b32_e32 v2, v92, v2
	v_lshlrev_b32_e32 v1, 2, v1
	v_and_b32_e32 v1, 12, v1
	v_mul_u32_u24_e32 v2, 0x88, v2
	v_add_lshl_u32 v102, v2, v1, 1
	v_mov_b32_e32 v2, v0
	v_mov_b32_e32 v3, v0
	v_cmp_eq_u32_e64 s[38:39], 0, v10
	v_mul_u32_u24_e32 v101, 0x110, v4
	v_mov_b32_e32 v1, v0
	v_mov_b64_e32 v[34:35], v[2:3]
	v_mov_b64_e32 v[30:31], v[2:3]
	v_mov_b64_e32 v[26:27], v[2:3]
	v_mov_b64_e32 v[22:23], v[2:3]
	v_mov_b64_e32 v[18:19], v[2:3]
	v_mov_b64_e32 v[14:15], v[2:3]
	v_mov_b64_e32 v[10:11], v[2:3]
	v_mov_b64_e32 v[6:7], v[2:3]
	s_mov_b32 s26, 0
	v_add_u32_e32 v99, 0x2200, v98
	s_not_b32 s27, s16
	v_mov_b32_e32 v103, 0
	s_mov_b64 s[18:19], 0
	v_mov_b64_e32 v[32:33], v[0:1]
	v_mov_b64_e32 v[28:29], v[0:1]
	v_mov_b64_e32 v[24:25], v[0:1]
	v_mov_b64_e32 v[20:21], v[0:1]
	v_mov_b64_e32 v[16:17], v[0:1]
	v_mov_b64_e32 v[12:13], v[0:1]
	v_mov_b64_e32 v[8:9], v[0:1]
	v_mov_b64_e32 v[4:5], v[0:1]
	s_branch .LBB0_183
.LBB0_180:
	s_or_b64 exec, exec, s[20:21]
	s_waitcnt lgkmcnt(0)
	s_and_b64 s[20:21], s[40:41], exec

.LBB0_183:
	s_mul_i32 s12, s26, 0x8800
	s_add_i32 s12, s12, 0
	v_add_u32_e32 v1, s12, v98
	v_add_u32_e32 v2, s12, v99
	s_lshl_b32 s13, s26, 5
	s_waitcnt vmcnt(4)
	s_cmp_lg_u32 s26, 0
	s_cbranch_scc1 .Lattn_wrB
	ds_write_b128 v1, v[64:67]
	ds_write_b128 v2, v[60:63]
	ds_write_b128 v1, v[56:59] offset:17408
	ds_write_b128 v2, v[52:55] offset:17408
	s_branch .Lattn_wr_done
.Lattn_wrB:
	ds_write_b128 v1, v[216:219]
	ds_write_b128 v2, v[236:239]
	ds_write_b128 v1, v[232:235] offset:17408
	ds_write_b128 v2, v[240:243] offset:17408
.Lattn_wr_done:
	s_and_saveexec_b64 s[16:17], s[38:39]
	v_cndmask_b32_e64 v1, 0, 1, s[18:19]
	v_add_u32_e32 v2, s13, v96
	ds_write_b32 v2, v1
	s_or_b64 exec, exec, s[16:17]
	s_add_i32 s13, s13, 0
	s_add_i32 s13, s13, 0x11000
	v_mov_b32_e32 v1, s13
	s_waitcnt lgkmcnt(0)
	s_barrier
	ds_read_b128 v[68:71], v1
	ds_read_b128 v[104:107], v1 offset:16
	s_mov_b64 s[16:17], -1
	s_waitcnt lgkmcnt(1)
	v_and_b32_e32 v1, v68, v69
	v_and_b32_e32 v1, v1, v70
	v_and_b32_e32 v1, v1, v71
	s_waitcnt lgkmcnt(0)
	v_and_b32_e32 v1, v1, v104
	v_and_b32_e32 v1, v1, v105
	v_and_b32_e32 v1, v1, v106
	v_and_b32_e32 v1, v1, v107
	v_and_b32_e32 v1, 1, v1
	v_cmp_eq_u32_e32 vcc, 1, v1
	s_cbranch_vccz .LBB0_187
	s_and_b64 vcc, exec, s[16:17]
	s_cbranch_vccz .LBB0_183
	s_branch .LBB0_177
.LBB0_187:
	s_sub_i32 s13, s25, 64
	s_max_i32 s13, s13, 0
	v_add_u32_e32 v1, s13, v97
	v_mad_i64_i32 v[2:3], s[16:17], v1, s11, v[90:91]
	v_add_co_u32_e32 v200, vcc, 0x3000, v2
	s_nop 1
	v_addc_co_u32_e32 v201, vcc, 0, v3, vcc
	v_add_co_u32_e32 v202, vcc, 0x4000, v2
	s_nop 1
	v_addc_co_u32_e32 v203, vcc, 0, v3, vcc
	v_add_co_u32_e32 v204, vcc, 0xd3000, v2
	s_nop 1
	v_addc_co_u32_e32 v205, vcc, 0, v3, vcc
	v_add_co_u32_e32 v2, vcc, 0xd4000, v2
	s_nop 1
	v_addc_co_u32_e32 v3, vcc, 0, v3, vcc
	s_cmp_lg_u32 s26, 0
	s_cbranch_scc1 .Lattn_ldB
	global_load_dwordx4 v[64:67], v[200:201], off offset:2048
	global_load_dwordx4 v[56:59], v[202:203], off offset:2048
	global_load_dwordx4 v[60:63], v[204:205], off offset:2048
	global_load_dwordx4 v[52:55], v[2:3], off offset:2048
	s_branch .LBB0_189
.Lattn_ldB:
	global_load_dwordx4 v[216:219], v[200:201], off offset:2048
	global_load_dwordx4 v[232:235], v[202:203], off offset:2048
	global_load_dwordx4 v[236:239], v[204:205], off offset:2048
	global_load_dwordx4 v[240:243], v[2:3], off offset:2048
.LBB0_189:
	s_xor_b64 s[20:21], s[18:19], -1
	s_mov_b64 s[18:19], -1
	s_and_saveexec_b64 s[16:17], s[20:21]
	s_cbranch_execz .LBB0_182
	s_add_i32 s13, s25, 64
	v_cmp_le_i32_e32 vcc, s13, v93
	s_mov_b64 s[20:21], 0
	s_and_saveexec_b64 s[18:19], vcc
	s_cbranch_execz .LBB0_181
	v_add_u32_e32 v68, s12, v100
	v_mov_b32_e32 v2, v0
	v_mov_b32_e32 v3, v0
	s_add_i32 s13, s25, 0x70
	v_mov_b32_e32 v1, v0
	v_add_u32_e32 v105, v68, v101
	v_mov_b64_e32 v[70:71], v[2:3]
	v_cmp_le_u32_e64 s[22:23], s13, v93
	v_add_u32_e32 v104, s25, v92
	v_mov_b64_e32 v[68:69], v[0:1]
	v_add_u32_e32 v196, s12, v102
	s_setprio 1
	ds_read_b128 v[116:119], v105 offset:13056
	ds_read_b128 v[120:123], v105 offset:13120
	ds_read_b128 v[124:127], v105 offset:13184
	ds_read_b128 v[128:131], v105 offset:13248
	ds_read_b128 v[132:135], v105 offset:8704
	ds_read_b128 v[136:139], v105 offset:8768
	ds_read_b128 v[140:143], v105 offset:8832
	ds_read_b128 v[144:147], v105 offset:8896
	ds_read_b128 v[148:151], v105 offset:4352
	ds_read_b128 v[152:155], v105 offset:4416
	ds_read_b128 v[156:159], v105 offset:4480
	ds_read_b128 v[160:163], v105 offset:4544
	s_waitcnt lgkmcnt(11)
	v_mfma_f32_16x16x32_bf16 v[180:183], v[116:119], v[48:51], 0
	s_waitcnt lgkmcnt(10)
	v_mfma_f32_16x16x32_bf16 v[180:183], v[120:123], v[44:47], v[180:183]
	s_waitcnt lgkmcnt(9)
	v_mfma_f32_16x16x32_bf16 v[180:183], v[124:127], v[40:43], v[180:183]
	s_waitcnt lgkmcnt(8)
	v_mfma_f32_16x16x32_bf16 v[180:183], v[128:131], v[36:39], v[180:183]
	ds_read_b128 v[164:167], v105
	ds_read_b128 v[168:171], v105 offset:64
	ds_read_b128 v[172:175], v105 offset:128
	ds_read_b128 v[176:179], v105 offset:192
	s_waitcnt lgkmcnt(11)
	v_mfma_f32_16x16x32_bf16 v[184:187], v[132:135], v[48:51], 0
	s_waitcnt lgkmcnt(10)
	v_mfma_f32_16x16x32_bf16 v[184:187], v[136:139], v[44:47], v[184:187]
	s_waitcnt lgkmcnt(9)
	v_mfma_f32_16x16x32_bf16 v[184:187], v[140:143], v[40:43], v[184:187]
	s_waitcnt lgkmcnt(8)
	v_mfma_f32_16x16x32_bf16 v[184:187], v[144:147], v[36:39], v[184:187]
	ds_read_b64_tr_b16 v[116:117], v196 offset:26112
	ds_read_b64_tr_b16 v[118:119], v196 offset:30464
	ds_read_b64_tr_b16 v[120:121], v196 offset:26144
	ds_read_b64_tr_b16 v[122:123], v196 offset:30496
	s_waitcnt lgkmcnt(11)
	v_mfma_f32_16x16x32_bf16 v[188:191], v[148:151], v[48:51], 0
	s_waitcnt lgkmcnt(10)
	v_mfma_f32_16x16x32_bf16 v[188:191], v[152:155], v[44:47], v[188:191]
	s_waitcnt lgkmcnt(9)
	v_mfma_f32_16x16x32_bf16 v[188:191], v[156:159], v[40:43], v[188:191]
	s_waitcnt lgkmcnt(8)
	v_mfma_f32_16x16x32_bf16 v[188:191], v[160:163], v[36:39], v[188:191]
	ds_read_b64_tr_b16 v[124:125], v196 offset:26176
	ds_read_b64_tr_b16 v[126:127], v196 offset:30528
	ds_read_b64_tr_b16 v[128:129], v196 offset:26208
	ds_read_b64_tr_b16 v[130:131], v196 offset:30560
	s_waitcnt lgkmcnt(11)
	v_mfma_f32_16x16x32_bf16 v[192:195], v[164:167], v[48:51], 0
	s_waitcnt lgkmcnt(10)
	v_mfma_f32_16x16x32_bf16 v[192:195], v[168:171], v[44:47], v[192:195]
	s_waitcnt lgkmcnt(9)
	v_mfma_f32_16x16x32_bf16 v[192:195], v[172:175], v[40:43], v[192:195]
	s_waitcnt lgkmcnt(8)
	v_mfma_f32_16x16x32_bf16 v[192:195], v[176:179], v[36:39], v[192:195]
	ds_read_b64_tr_b16 v[132:133], v196 offset:26240
	ds_read_b64_tr_b16 v[134:135], v196 offset:30592
	ds_read_b64_tr_b16 v[136:137], v196 offset:26272
	ds_read_b64_tr_b16 v[138:139], v196 offset:30624
	ds_read_b64_tr_b16 v[140:141], v196 offset:26304
	ds_read_b64_tr_b16 v[142:143], v196 offset:30656
	s_setprio 0
	s_and_saveexec_b64 s[48:49], s[22:23]
	s_cbranch_execz .LBB0_193
	v_mov_b64_e32 v[68:69], v[180:181]
	v_mov_b64_e32 v[70:71], v[182:183]
	v_pk_mul_f32 v[2:3], v[68:69], s[72:73] op_sel_hi:[1,0]
	v_pk_mul_f32 v[106:107], v[70:71], s[72:73] op_sel_hi:[1,0]
	v_exp_f32_e64 v108, -|v2|
	v_exp_f32_e64 v109, -|v3|
	v_exp_f32_e64 v110, -|v106|
	v_exp_f32_e64 v111, -|v107|
	v_max_f32_e32 v2, 0, v2
	v_pk_add_f32 v[108:109], v[108:109], 1.0 op_sel_hi:[1,0]
	v_max_f32_e32 v3, 0, v3
	v_pk_add_f32 v[110:111], v[110:111], 1.0 op_sel_hi:[1,0]
	v_log_f32_e32 v108, v108
	v_log_f32_e32 v109, v109
	v_log_f32_e32 v110, v110
	v_log_f32_e32 v111, v111
	v_max_f32_e32 v106, 0, v106
	v_max_f32_e32 v107, 0, v107
	v_add_u32_e32 v1, 0x70, v104
	v_pk_add_f32 v[2:3], v[2:3], v[108:109]
	v_pk_add_f32 v[106:107], v[106:107], v[110:111]
	v_add_u32_e32 v108, 0x71, v104
	v_add_u32_e32 v109, 0x72, v104
	v_add_u32_e32 v110, 0x73, v104
	v_cmp_lt_i32_e32 vcc, v1, v88
	v_cmp_lt_i32_e64 s[40:41], v108, v88
	v_cmp_lt_i32_e64 s[42:43], v109, v88
	v_cmp_lt_i32_e64 s[44:45], v110, v88
	v_cndmask_b32_e32 v1, 0, v2, vcc
	v_cndmask_b32_e64 v108, 0, v3, s[40:41]
	v_cndmask_b32_e64 v2, 0, v106, s[42:43]
	v_cndmask_b32_e64 v3, 0, v107, s[44:45]
	v_add_f32_e32 v2, v2, v3
	v_add_f32_e32 v107, v108, v2
	v_add_f32_e32 v106, v1, v107
	v_mov_b32_e32 v1, v106
	v_mov_b32_e32 v108, v106
	s_nop 1
	v_permlane16_swap_b32_e32 v1, v108
	v_add_f32_e32 v1, v1, v108
	v_mov_b32_e32 v109, v1
	s_nop 1
	v_permlane32_swap_b32_e32 v1, v109
	v_mul_f32_e32 v110, v95, v109
	v_fmac_f32_e32 v110, v94, v108
	v_add_f32_e32 v108, v103, v110
	v_pk_fma_f32 v[68:69], v[68:69], s[72:73], v[108:109] op_sel_hi:[1,0,0] neg_lo:[0,0,1] neg_hi:[0,0,1]
	v_add_f32_e32 v1, v1, v109
	v_pk_add_f32 v[68:69], v[68:69], v[106:107] neg_lo:[0,1] neg_hi:[0,1]
	v_pk_fma_f32 v[70:71], v[70:71], s[72:73], v[108:109] op_sel_hi:[1,0,0] neg_lo:[0,0,1] neg_hi:[0,0,1]
	v_add_f32_e32 v103, v103, v1
	v_pk_add_f32 v[2:3], v[70:71], v[2:3] neg_lo:[0,1] neg_hi:[0,1]
	v_exp_f32_e32 v1, v68
	v_exp_f32_e32 v68, v69
	v_exp_f32_e32 v2, v2
	v_exp_f32_e32 v3, v3
	s_mov_b32 s13, 0x43170000
	v_cndmask_b32_e32 v1, 0, v1, vcc
	v_cmp_le_f32_e32 vcc, s13, v103
	v_cndmask_b32_e64 v68, 0, v68, s[40:41]
	v_cndmask_b32_e64 v69, 0, v2, s[42:43]
	v_cndmask_b32_e64 v3, 0, v3, s[44:45]
	s_cmp_eq_u64 vcc, exec
	v_cvt_pk_bf16_f32 v2, v1, v68
	v_cvt_pk_bf16_f32 v3, v69, v3
	v_mov_b32_e32 v1, v0
	s_cselect_b64 s[20:21], -1, 0
	v_mov_b64_e32 v[70:71], v[2:3]
	s_and_b64 s[20:21], s[20:21], exec
	v_mov_b64_e32 v[68:69], v[0:1]
.LBB0_193:
	s_or_b64 exec, exec, s[48:49]
	s_add_i32 s13, s25, 0x60
	v_cmp_le_u32_e32 vcc, s13, v93
	s_xor_b64 s[40:41], s[20:21], -1
	s_and_b64 s[40:41], s[40:41], vcc
	s_and_saveexec_b64 s[48:49], s[40:41]
	s_cbranch_execz .LBB0_195
	v_mov_b64_e32 v[106:107], v[184:185]
	v_mov_b64_e32 v[108:109], v[186:187]
	v_pk_mul_f32 v[2:3], v[106:107], s[72:73] op_sel_hi:[1,0]
	v_pk_mul_f32 v[68:69], v[108:109], s[72:73] op_sel_hi:[1,0]
	v_exp_f32_e64 v110, -|v2|
	v_exp_f32_e64 v111, -|v3|
	v_exp_f32_e64 v112, -|v68|
	v_exp_f32_e64 v113, -|v69|
	v_max_f32_e32 v2, 0, v2
	v_pk_add_f32 v[110:111], v[110:111], 1.0 op_sel_hi:[1,0]
	v_max_f32_e32 v3, 0, v3
	v_pk_add_f32 v[112:113], v[112:113], 1.0 op_sel_hi:[1,0]
	v_log_f32_e32 v110, v110
	v_log_f32_e32 v111, v111
	v_log_f32_e32 v112, v112
	v_log_f32_e32 v113, v113
	v_max_f32_e32 v68, 0, v68
	v_max_f32_e32 v69, 0, v69
	v_add_u32_e32 v1, 0x60, v104
	v_pk_add_f32 v[2:3], v[2:3], v[110:111]
	v_pk_add_f32 v[68:69], v[68:69], v[112:113]
	v_add_u32_e32 v110, 0x61, v104
	v_add_u32_e32 v111, 0x62, v104
	v_add_u32_e32 v112, 0x63, v104
	v_cmp_lt_i32_e32 vcc, v1, v88
	v_cmp_lt_i32_e64 s[40:41], v110, v88
	v_cmp_lt_i32_e64 s[42:43], v111, v88
	v_cmp_lt_i32_e64 s[44:45], v112, v88
	v_cndmask_b32_e32 v1, 0, v2, vcc
	v_cndmask_b32_e64 v110, 0, v3, s[40:41]
	v_cndmask_b32_e64 v2, 0, v68, s[42:43]
	v_cndmask_b32_e64 v3, 0, v69, s[44:45]
	v_add_f32_e32 v2, v2, v3
	v_add_f32_e32 v69, v110, v2
	v_add_f32_e32 v68, v1, v69
	v_mov_b32_e32 v1, v68
	v_mov_b32_e32 v110, v68
	s_nop 1
	v_permlane16_swap_b32_e32 v1, v110
	v_add_f32_e32 v1, v1, v110
	v_mov_b32_e32 v111, v1
	s_nop 1
	v_permlane32_swap_b32_e32 v1, v111
	v_mul_f32_e32 v112, v95, v111
	v_fmac_f32_e32 v112, v94, v110
	v_add_f32_e32 v110, v103, v112
	v_pk_fma_f32 v[106:107], v[106:107], s[72:73], v[110:111] op_sel_hi:[1,0,0] neg_lo:[0,0,1] neg_hi:[0,0,1]
	v_add_f32_e32 v1, v1, v111
	v_pk_add_f32 v[68:69], v[106:107], v[68:69] neg_lo:[0,1] neg_hi:[0,1]
	v_add_f32_e32 v103, v103, v1
	v_exp_f32_e32 v1, v68
	v_exp_f32_e32 v68, v69
	v_pk_fma_f32 v[106:107], v[108:109], s[72:73], v[110:111] op_sel_hi:[1,0,0] neg_lo:[0,0,1] neg_hi:[0,0,1]
	s_mov_b32 s13, 0x43170000
	v_pk_add_f32 v[2:3], v[106:107], v[2:3] neg_lo:[0,1] neg_hi:[0,1]
	v_cndmask_b32_e32 v1, 0, v1, vcc
	v_cmp_le_f32_e32 vcc, s13, v103
	v_exp_f32_e32 v2, v2
	v_exp_f32_e32 v3, v3
	s_cmp_eq_u64 vcc, exec
	v_cndmask_b32_e64 v68, 0, v68, s[40:41]
	s_cselect_b64 s[40:41], -1, 0
	s_andn2_b64 s[20:21], s[20:21], exec
	s_and_b64 s[40:41], s[40:41], exec
	s_or_b64 s[22:23], s[22:23], exec
	s_or_b64 s[20:21], s[20:21], s[40:41]
	v_cndmask_b32_e64 v2, 0, v2, s[42:43]
	v_cndmask_b32_e64 v3, 0, v3, s[44:45]
	v_cvt_pk_bf16_f32 v68, v1, v68
	v_cvt_pk_bf16_f32 v69, v2, v3
.LBB0_195:
	s_or_b64 exec, exec, s[48:49]
	v_add_u32_e32 v106, s12, v102
	s_and_saveexec_b64 s[40:41], s[22:23]
	s_cbranch_execz .LBB0_197
	s_setprio 1
	s_waitcnt lgkmcnt(0)
	ds_read_b64_tr_b16 v[144:145], v196 offset:26336
	ds_read_b64_tr_b16 v[146:147], v196 offset:30688
	v_mfma_f32_16x16x32_bf16 v[32:35], v[116:119], v[68:71], v[32:35]
	v_mfma_f32_16x16x32_bf16 v[28:31], v[120:123], v[68:71], v[28:31]
	v_mfma_f32_16x16x32_bf16 v[24:27], v[124:127], v[68:71], v[24:27]
	v_mfma_f32_16x16x32_bf16 v[20:23], v[128:131], v[68:71], v[20:23]
	v_mfma_f32_16x16x32_bf16 v[16:19], v[132:135], v[68:71], v[16:19]
	v_mfma_f32_16x16x32_bf16 v[12:15], v[136:139], v[68:71], v[12:15]
	v_mfma_f32_16x16x32_bf16 v[8:11], v[140:143], v[68:71], v[8:11]
	s_waitcnt lgkmcnt(0)
	v_mfma_f32_16x16x32_bf16 v[4:7], v[144:147], v[68:71], v[4:7]
	s_setprio 0
.LBB0_197:
	s_or_b64 exec, exec, s[40:41]
	s_waitcnt lgkmcnt(0)
	ds_read_b64_tr_b16 v[148:149], v196 offset:17408
	ds_read_b64_tr_b16 v[150:151], v196 offset:21760
	ds_read_b64_tr_b16 v[152:153], v196 offset:17440
	ds_read_b64_tr_b16 v[154:155], v196 offset:21792
	ds_read_b64_tr_b16 v[156:157], v196 offset:17472
	ds_read_b64_tr_b16 v[158:159], v196 offset:21824
	ds_read_b64_tr_b16 v[160:161], v196 offset:17504
	ds_read_b64_tr_b16 v[162:163], v196 offset:21856
	ds_read_b64_tr_b16 v[164:165], v196 offset:17536
	ds_read_b64_tr_b16 v[166:167], v196 offset:21888
	ds_read_b64_tr_b16 v[168:169], v196 offset:17568
	ds_read_b64_tr_b16 v[170:171], v196 offset:21920
	ds_read_b64_tr_b16 v[172:173], v196 offset:17600
	ds_read_b64_tr_b16 v[174:175], v196 offset:21952
	s_add_i32 s12, s25, 0x50
	v_cmp_gt_u32_e32 vcc, s12, v93
	v_mov_b32_e32 v2, v0
	v_mov_b32_e32 v3, v0
	s_or_b64 s[12:13], s[20:21], vcc
	v_mov_b32_e32 v1, v0
	v_mov_b64_e32 v[70:71], v[2:3]
	s_xor_b64 s[22:23], s[12:13], -1
	v_mov_b64_e32 v[68:69], v[0:1]
	s_and_saveexec_b64 s[48:49], s[22:23]
	s_cbranch_execz .LBB0_199
	v_mov_b64_e32 v[68:69], v[188:189]
	v_mov_b64_e32 v[70:71], v[190:191]
	v_pk_mul_f32 v[2:3], v[68:69], s[72:73] op_sel_hi:[1,0]
	v_pk_mul_f32 v[108:109], v[70:71], s[72:73] op_sel_hi:[1,0]
	v_exp_f32_e64 v110, -|v2|
	v_exp_f32_e64 v111, -|v3|
	v_exp_f32_e64 v112, -|v108|
	v_exp_f32_e64 v113, -|v109|
	v_max_f32_e32 v2, 0, v2
	v_pk_add_f32 v[110:111], v[110:111], 1.0 op_sel_hi:[1,0]
	v_max_f32_e32 v3, 0, v3
	v_pk_add_f32 v[112:113], v[112:113], 1.0 op_sel_hi:[1,0]
	v_log_f32_e32 v110, v110
	v_log_f32_e32 v111, v111
	v_log_f32_e32 v112, v112
	v_log_f32_e32 v113, v113
	v_add_u32_e32 v1, 0x50, v104
	v_max_f32_e32 v108, 0, v108
	v_max_f32_e32 v109, 0, v109
	v_pk_add_f32 v[2:3], v[2:3], v[110:111]
	v_add_u32_e32 v107, 0x51, v104
	v_add_u32_e32 v110, 0x52, v104
	v_add_u32_e32 v111, 0x53, v104
	v_pk_add_f32 v[108:109], v[108:109], v[112:113]
	v_cmp_lt_i32_e32 vcc, v1, v88
	v_cmp_lt_i32_e64 s[40:41], v107, v88
	v_cmp_lt_i32_e64 s[42:43], v110, v88
	v_cmp_lt_i32_e64 s[44:45], v111, v88
	v_cndmask_b32_e32 v1, 0, v2, vcc
	v_cndmask_b32_e64 v107, 0, v3, s[40:41]
	v_cndmask_b32_e64 v2, 0, v108, s[42:43]
	v_cndmask_b32_e64 v3, 0, v109, s[44:45]
	v_add_f32_e32 v2, v2, v3
	v_add_f32_e32 v109, v107, v2
	v_add_f32_e32 v108, v1, v109
	v_mov_b32_e32 v1, v108
	v_mov_b32_e32 v107, v108
	s_nop 1
	v_permlane16_swap_b32_e32 v1, v107
	v_add_f32_e32 v1, v1, v107
	v_mov_b32_e32 v111, v1
	s_nop 1
	v_permlane32_swap_b32_e32 v1, v111
	v_mul_f32_e32 v110, v95, v111
	v_fmac_f32_e32 v110, v94, v107
	v_add_f32_e32 v110, v103, v110
	v_pk_fma_f32 v[68:69], v[68:69], s[72:73], v[110:111] op_sel_hi:[1,0,0] neg_lo:[0,0,1] neg_hi:[0,0,1]
	v_add_f32_e32 v1, v1, v111
	v_pk_add_f32 v[68:69], v[68:69], v[108:109] neg_lo:[0,1] neg_hi:[0,1]
	v_add_f32_e32 v103, v103, v1
	v_pk_fma_f32 v[70:71], v[70:71], s[72:73], v[110:111] op_sel_hi:[1,0,0] neg_lo:[0,0,1] neg_hi:[0,0,1]
	v_exp_f32_e32 v1, v68
	v_pk_add_f32 v[2:3], v[70:71], v[2:3] neg_lo:[0,1] neg_hi:[0,1]
	v_exp_f32_e32 v68, v69
	v_exp_f32_e32 v2, v2
	v_exp_f32_e32 v3, v3
	s_mov_b32 s12, 0x43170000
	v_cndmask_b32_e32 v1, 0, v1, vcc
	v_cmp_le_f32_e32 vcc, s12, v103
	s_cmp_eq_u64 vcc, exec
	v_cndmask_b32_e64 v68, 0, v68, s[40:41]
	v_cndmask_b32_e64 v69, 0, v2, s[42:43]
	v_cndmask_b32_e64 v3, 0, v3, s[44:45]
	s_cselect_b64 s[12:13], -1, 0
	v_cvt_pk_bf16_f32 v2, v1, v68
	v_cvt_pk_bf16_f32 v3, v69, v3
	v_mov_b32_e32 v1, v0
	s_andn2_b64 s[20:21], s[20:21], exec
	s_and_b64 s[12:13], s[12:13], exec
	v_mov_b64_e32 v[70:71], v[2:3]
	s_or_b64 s[20:21], s[20:21], s[12:13]
	v_mov_b64_e32 v[68:69], v[0:1]
.LBB0_199:
	s_or_b64 exec, exec, s[48:49]
	s_mov_b64 s[40:41], -1
	s_xor_b64 s[12:13], s[20:21], -1
	s_and_saveexec_b64 s[20:21], s[12:13]
	s_cbranch_execz .LBB0_201
	v_mov_b64_e32 v[108:109], v[192:193]
	v_mov_b64_e32 v[110:111], v[194:195]
	v_pk_mul_f32 v[2:3], v[108:109], s[72:73] op_sel_hi:[1,0]
	v_pk_mul_f32 v[68:69], v[110:111], s[72:73] op_sel_hi:[1,0]
	v_exp_f32_e64 v112, -|v2|
	v_exp_f32_e64 v113, -|v3|
	v_exp_f32_e64 v114, -|v68|
	v_exp_f32_e64 v115, -|v69|
	v_add_u32_e32 v1, 64, v104
	v_pk_add_f32 v[112:113], v[112:113], 1.0 op_sel_hi:[1,0]
	v_max_f32_e32 v2, 0, v2
	v_pk_add_f32 v[114:115], v[114:115], 1.0 op_sel_hi:[1,0]
	v_log_f32_e32 v112, v112
	v_log_f32_e32 v113, v113
	v_log_f32_e32 v114, v114
	v_log_f32_e32 v115, v115
	v_max_f32_e32 v3, 0, v3
	v_max_f32_e32 v68, 0, v68
	v_max_f32_e32 v69, 0, v69
	v_add_u32_e32 v105, 0x41, v104
	v_add_u32_e32 v107, 0x42, v104
	v_add_u32_e32 v104, 0x43, v104
	v_pk_add_f32 v[2:3], v[2:3], v[112:113]
	v_pk_add_f32 v[68:69], v[68:69], v[114:115]
	v_cmp_lt_i32_e32 vcc, v1, v88
	v_cmp_lt_i32_e64 s[40:41], v105, v88
	v_cmp_lt_i32_e64 s[42:43], v107, v88
	v_cmp_lt_i32_e64 s[44:45], v104, v88
	v_cndmask_b32_e32 v1, 0, v2, vcc
	v_cndmask_b32_e64 v105, 0, v3, s[40:41]
	v_cndmask_b32_e64 v2, 0, v68, s[42:43]
	v_cndmask_b32_e64 v3, 0, v69, s[44:45]
	v_add_f32_e32 v2, v2, v3
	v_add_f32_e32 v69, v105, v2
	v_add_f32_e32 v68, v1, v69
	v_mov_b32_e32 v1, v68
	v_mov_b32_e32 v104, v68
	s_nop 1
	v_permlane16_swap_b32_e32 v1, v104
	v_add_f32_e32 v1, v1, v104
	v_mov_b32_e32 v105, v1
	s_nop 1
	v_permlane32_swap_b32_e32 v1, v105
	v_mul_f32_e32 v107, v95, v105
	v_fmac_f32_e32 v107, v94, v104
	v_add_f32_e32 v104, v103, v107
	v_pk_fma_f32 v[108:109], v[108:109], s[72:73], v[104:105] op_sel_hi:[1,0,0] neg_lo:[0,0,1] neg_hi:[0,0,1]
	v_add_f32_e32 v1, v1, v105
	v_pk_add_f32 v[68:69], v[108:109], v[68:69] neg_lo:[0,1] neg_hi:[0,1]
	v_add_f32_e32 v103, v103, v1
	v_exp_f32_e32 v1, v68
	v_pk_fma_f32 v[104:105], v[110:111], s[72:73], v[104:105] op_sel_hi:[1,0,0] neg_lo:[0,0,1] neg_hi:[0,0,1]
	v_exp_f32_e32 v68, v69
	v_pk_add_f32 v[2:3], v[104:105], v[2:3] neg_lo:[0,1] neg_hi:[0,1]
	s_mov_b32 s12, 0x43170000
	v_exp_f32_e32 v2, v2
	v_exp_f32_e32 v3, v3
	v_cndmask_b32_e32 v1, 0, v1, vcc
	v_cmp_le_f32_e32 vcc, s12, v103
	s_cmp_eq_u64 vcc, exec
	s_cselect_b64 s[12:13], -1, 0
	v_cndmask_b32_e64 v68, 0, v68, s[40:41]
	s_or_b64 s[22:23], s[22:23], exec
	s_orn2_b64 s[40:41], s[12:13], exec
	v_cndmask_b32_e64 v2, 0, v2, s[42:43]
	v_cndmask_b32_e64 v3, 0, v3, s[44:45]
	v_cvt_pk_bf16_f32 v68, v1, v68
	v_cvt_pk_bf16_f32 v69, v2, v3
.LBB0_201:
	s_or_b64 exec, exec, s[20:21]
	s_and_saveexec_b64 s[20:21], s[22:23]
	s_cbranch_execz .LBB0_180
	s_setprio 1
	s_waitcnt lgkmcnt(0)
	ds_read_b64_tr_b16 v[176:177], v196 offset:17632
	ds_read_b64_tr_b16 v[178:179], v196 offset:21984
	v_mfma_f32_16x16x32_bf16 v[32:35], v[148:151], v[68:71], v[32:35]
	v_mfma_f32_16x16x32_bf16 v[28:31], v[152:155], v[68:71], v[28:31]
	v_mfma_f32_16x16x32_bf16 v[24:27], v[156:159], v[68:71], v[24:27]
	v_mfma_f32_16x16x32_bf16 v[20:23], v[160:163], v[68:71], v[20:23]
	v_mfma_f32_16x16x32_bf16 v[16:19], v[164:167], v[68:71], v[16:19]
	v_mfma_f32_16x16x32_bf16 v[12:15], v[168:171], v[68:71], v[12:15]
	v_mfma_f32_16x16x32_bf16 v[8:11], v[172:175], v[68:71], v[8:11]
	s_waitcnt lgkmcnt(0)
	v_mfma_f32_16x16x32_bf16 v[4:7], v[176:179], v[68:71], v[4:7]
	s_setprio 0
	s_branch .LBB0_180
